# grid barrier: L1 invalidate (buffer_inv sc1) moved from after release to each block's arrival (waited before arrival atomic)
# speedup vs baseline: 1.0283x; 1.0224x over previous
; DI void xcd_barrier(const XcdBarrier& b) {
;   asm volatile("s_waitcnt vmcnt(0)" ::: "memory");
;   __syncthreads();
;   if (threadIdx.x == 0) {
;     unsigned* bar = b.bar;
;     __builtin_amdgcn_s_waitcnt(0);
;     unsigned nloc = b.st[0], nx = b.st[1];
;     if (nloc == 0u) { xcd_barrier_complete(bar, b.x, nloc, nx); b.st[0] = nloc; b.st[1] = nx; }
.LBB0_1787:
	v_readlane_b32 s4, v255, 27
	s_cmp_eq_u32 s4, 24
	s_cbranch_scc1 .LBB0_1841
	s_waitcnt vmcnt(0)
	s_waitcnt lgkmcnt(0)
	s_barrier
	s_and_saveexec_b64 s[38:39], s[80:81]
	s_cbranch_execz .LBB0_1840
	s_waitcnt vmcnt(0) expcnt(0) lgkmcnt(0)
	buffer_inv sc1
	ds_read_b32 v2, v201
	ds_read_b32 v0, v202
	s_waitcnt lgkmcnt(1)
	v_cmp_ne_u32_e32 vcc, 0, v2
	s_cbranch_vccnz .LBB0_1804
	s_mov_b32 s4, 1
	s_branch .LBB0_1792

; DI unsigned xb_add(unsigned* p, unsigned v) { return __hip_atomic_fetch_add(p, v, __ATOMIC_RELAXED, __HIP_MEMORY_SCOPE_AGENT); }
; DI void xcd_barrier(const XcdBarrier& b) {
;     ...
;     const unsigned old = xb_add(&bar[XB_XSUB(b.x)], 1u);
;     const unsigned gen = old / nloc;
.LBB0_1804:
	s_mov_b64 s[42:43], exec
	v_mbcnt_lo_u32_b32 v1, s42, 0
	v_mbcnt_hi_u32_b32 v1, s43, v1
	v_cmp_eq_u32_e32 vcc, 0, v1
	s_and_saveexec_b64 s[40:41], vcc
	s_cbranch_execz .LBB0_1806
	s_bcnt1_i32_b64 s4, s[42:43]
	v_mov_b32_e32 v3, s4
	v_readlane_b32 s4, v254, 42
	v_readlane_b32 s5, v254, 43
	s_waitcnt vmcnt(0)
	s_nop 4
	global_atomic_add v3, v183, v3, s[4:5] sc0

; DI unsigned xb_ld(unsigned* p) { return __hip_atomic_load(p, __ATOMIC_RELAXED, __HIP_MEMORY_SCOPE_AGENT); }
; #define XB_SPIN(cond, bar) do { unsigned _sp = 0; while (cond) { __builtin_amdgcn_s_sleep(1); \
;     if ((++_sp & 255u) == 0u) { if (xb_ld(&(bar)[XB_TMO])) break; if (_sp > XB_SPIN_CAP) { atomicAdd(&(bar)[XB_TMO], 1u); break; } } } } while (0)
; DI void xcd_barrier(const XcdBarrier& b) {
;     ...
;       XB_SPIN(xb_ld(&bar[XB_XGEN(b.x)]) == gen, bar);
;       __builtin_amdgcn_fence(__ATOMIC_ACQUIRE, "agent");
;       asm volatile("s_waitcnt vmcnt(0)" ::: "memory");
.LBB0_1819:
	s_or_b64 exec, exec, s[42:43]
	s_waitcnt vmcnt(0)
	s_waitcnt vmcnt(0)

; DI unsigned xb_ld(unsigned* p) { return __hip_atomic_load(p, __ATOMIC_RELAXED, __HIP_MEMORY_SCOPE_AGENT); }
; DI unsigned xb_add(unsigned* p, unsigned v) { return __hip_atomic_fetch_add(p, v, __ATOMIC_RELAXED, __HIP_MEMORY_SCOPE_AGENT); }
; #define XB_SPIN(cond, bar) do { unsigned _sp = 0; while (cond) { __builtin_amdgcn_s_sleep(1); \
;     if ((++_sp & 255u) == 0u) { if (xb_ld(&(bar)[XB_TMO])) break; if (_sp > XB_SPIN_CAP) { atomicAdd(&(bar)[XB_TMO], 1u); break; } } } } while (0)
; DI void xcd_barrier(const XcdBarrier& b) {
;     ...
;       else XB_SPIN(xb_ld(&bar[XB_TOPGEN]) == tg, bar);
;       __builtin_amdgcn_fence(__ATOMIC_ACQUIRE, "agent");
;       xb_add(&bar[XB_XGEN(b.x)], 1u);
.LBB0_1837:
	s_or_b64 exec, exec, s[40:41]
	s_mov_b64 s[40:41], exec
	v_mbcnt_lo_u32_b32 v0, s40, 0
	v_mbcnt_hi_u32_b32 v0, s41, v0
	v_cmp_eq_u32_e32 vcc, 0, v0
	s_waitcnt vmcnt(0)
	s_and_saveexec_b64 s[42:43], vcc
	s_cbranch_execz .LBB0_1839
	s_bcnt1_i32_b64 s4, s[40:41]
	v_mov_b32_e32 v0, s4
	v_readlane_b32 s4, v254, 44
	v_readlane_b32 s5, v254, 45
	s_nop 4
	global_atomic_add v183, v0, s[4:5]
